# combine output YC relocated from the Q/K scratch region to the (idle) PP region so the Hout->GU2 seam can also be group-local: 11 of 20 seams local
# baseline (speedup 1.0000x reference)
; template <int L> __device__ __forceinline__ void layer_body(const Args& args, LAS unsigned char* lds, const int G, const int lo, const int hi, const int wave_s, unsigned& nbar) {
;     ...
;                 const float* cw = args.in[9]; const bf16_t *GB = PBF(O_GB), *U = PBF(O_U), *OB = (const bf16_t*)outp; bf16_t* YC = PBF(O_YC); const float* LSE = PF32(WS_LSE);
;                 const int c8 = (tid & 127) * 8; const int tstride = G * 4;
;                 if (c8 < CW) {
;                     f32x4 wt[3][2];
; #pragma unroll
;                     for (int j = 0; j < 3; ++j) { wt[j][0] = *(const f32x4*)(cw + j * CW + c8); wt[j][1] = *(const f32x4*)(cw + j * CW + c8 + 4); }
;                     for (int tb = vcu * 4 + (tid >> 7); tb < T; tb += 4 * tstride) {
;                         u32x4 uw[4][3], gw_[4];
; #pragma unroll
;                         for (int q = 0; q < 4; ++q) { const int t = tb + q * tstride, sp = t & (SEQ - 1); if (t < T) {
; #pragma unroll
;                             for (int j = 0; j < 3; ++j) { const int back = 2 - j; uw[q][j] = (sp - back >= 0) ? *(const u32x4*)(U + (size_t)(t - back) * CW + c8) : (u32x4){0u, 0u, 0u, 0u}; }
;                             gw_[q] = *(const u32x4*)(GB + (size_t)t * CW + c8); } }
; #pragma unroll
;                         for (int q = 0; q < 4; ++q) { const int t = tb + q * tstride; if (t < T) {
;                             f32x4 y0 = {0.f, 0.f, 0.f, 0.f}, y1 = y0;
; #pragma unroll
;                             for (int j = 0; j < 3; ++j) { y0 += wt[j][0] * bf4_lo(uw[q][j]); y1 += wt[j][1] * bf4_hi(uw[q][j]); }
;                             y0 *= bf4_lo(gw_[q]); y1 *= bf4_hi(gw_[q]);
;                             *(u32x4*)(YC + (size_t)t * D + c8) = pack8(y0, y1); } }
;                     }
;                 } else {
;                     const int ch = c8 - CW, hd = ch >> 6;
;                     for (int tb = vcu * 4 + (tid >> 7); tb < T; tb += 4 * tstride) {
;                         u32x4 ow[4][3]; float lv[4][3];
; #pragma unroll
;                         for (int q = 0; q < 4; ++q) { const int t = tb + q * tstride; if (t < T) {
; #pragma unroll
;                             for (int g = 0; g < 3; ++g) { lv[q][g] = LSE[(size_t)g * T * NH + (size_t)t * NH + hd]; ow[q][g] = *(const u32x4*)(OB + (size_t)g * T * CW + (size_t)t * CW + ch); } } }
.LBB0_601:
	s_and_b32 s2, s79, 0xffffffc0
	v_add_u32_e32 v0, s2, v0
	v_lshlrev_b32_e32 v1, 3, v0
	s_add_u32 s14, s10, 0x19100000
	s_waitcnt vmcnt(0)
	v_and_b32_e32 v24, 0x3f8, v1
	s_movk_i32 s2, 0x1ff
	s_addc_u32 s15, s11, 0
	s_lshl_b32 s20, s92, 2
	v_cmp_lt_u32_e32 vcc, s2, v24
	s_and_saveexec_b64 s[2:3], vcc
	s_xor_b64 s[12:13], exec, s[2:3]
	s_cbranch_execz .LBB0_618
	v_ashrrev_i32_e32 v0, 7, v0
	v_lshl_add_u32 v60, s21, 2, v0
	s_mov_b32 s22, 0x8000
	v_cmp_gt_i32_e32 vcc, s22, v60
	s_and_saveexec_b64 s[16:17], vcc
	s_cbranch_execz .LBB0_617
	v_add_u32_e32 v0, 0xfffffe00, v24
	v_lshrrev_b32_e32 v1, 4, v0
	v_and_b32_e32 v2, 0xffffffc, v1
	v_mov_b32_e32 v3, 0
	v_lshl_add_u64 v[4:5], s[10:11], 0, v[2:3]
	s_mov_b64 s[2:3], 0x1f500000
	v_mov_b32_e32 v1, v3
	v_lshlrev_b32_e32 v2, 1, v24
	s_add_i32 s27, s20, s20
	v_lshl_add_u64 v[48:49], v[4:5], 0, s[2:3]
	v_lshl_add_u64 v[50:51], v[0:1], 1, s[8:9]
	v_lshl_add_u64 v[52:53], s[14:15], 0, v[2:3]
	s_lshl_b32 s23, s92, 3
	s_mul_i32 s24, s92, 12
	s_mov_b64 s[8:9], 0
	s_mov_b32 s25, 0x100000
	s_brev_b32 s26, 64
	s_add_i32 s27, s27, s20
	s_movk_i32 s28, 0x7fff
	s_branch .LBB0_605

; #define PG8_STAGE(bufoff, gbase, voff) do { _Pragma("unroll") for (int _i = 0; _i < 2; ++_i) \
;         __builtin_amdgcn_global_load_lds((const unsigned*)((const char*)(gbase) + (voff)[_i]), (LAS unsigned*)(lds + (bufoff) + ldsw + _i * 8192), 16, 0, 0); } while (0)
; #define PG8_WAIT_V(n) asm volatile("s_waitcnt vmcnt(" #n ")" ::: "memory")
; #define PG8_BAR __builtin_amdgcn_s_barrier()
; template <class Epi>
; __device__ __forceinline__ void gemm_phase(LAS unsigned char* lds, const int tid, const Gemm g, const StaticOrder& S, const Epi& E) {
;     const int wid = __builtin_amdgcn_readfirstlane(tid >> 6), lane = tid & 63, wr = wid >> 2, wc = wid & 3, fr = lane & 15, fq = lane >> 4;
;     const int K = g.K, nt = K / BK;
;     unsigned voffA[2], voffB[2];
; #pragma unroll
;     for (int i = 0; i < 2; ++i) { int R, C; stage_rc(tid * 16 + i * 8192, R, C); const int Rb = (R & ~31) + perm32(R & 31);
;         voffA[i] = (unsigned)(R * g.lda + C) * 2u; voffB[i] = (unsigned)(Rb * g.ldb + C) * 2u; }
;     const size_t kstep = (size_t)(BK * 2);
;     const size_t hstepA = (size_t)HALF * g.lda * 2, hstepB = (size_t)HALF * g.ldb * 2;
;     const size_t tstepA = 2 * hstepA, tstepB = 2 * hstepB;
;     const unsigned ldsw = (unsigned)wid * 1024u;
;     const int aoff = lds_byte(wr * 64 + fr, fq * 8), boff = lds_byte(wc * 32 + fr, fq * 8);
;     ...
;     Unit cur, nxt; int ui = 0;
;     if (!S.next(0, cur)) return;
;     f32x4 acc[2][2][4][2];
; #pragma unroll
;     for (int a = 0; a < 2; ++a)
; #pragma unroll
;         for (int b = 0; b < 2; ++b)
; #pragma unroll
;             for (int m = 0; m < 4; ++m)
; #pragma unroll
;                 for (int n = 0; n < 2; ++n) acc[a][b][m][n] = (f32x4){0.f, 0.f, 0.f, 0.f};
;     bf16x8 At[4][2], B0[2][2], B1[2][2];
;     const char* cA = (const char*)g.A + (size_t)cur.pm * tstepA + (size_t)(cur.pn >> g.a_grp_shift) * g.a_grp_bytes;
;     const char* cB = (const char*)g.Bt + (size_t)cur.pn * tstepB;
;     ...
;     PG8_STAGE(PG8_SB(0, 0), cB, voffB); PG8_STAGE(PG8_SB(0, 1), cB + hstepB, voffB); PG8_STAGE(PG8_SA(0, 0), cA, voffA); PG8_STAGE(PG8_SA(0, 1), cA + hstepA, voffA);
;     if (wr == 1) PG8_BAR;
;     PG8_WAIT_V(2); PG8_BAR;
;     PG8_STAGE(PG8_SB(1, 0), cB + kstep, voffB); PG8_STAGE(PG8_SA(1, 0), cA + kstep, voffA); PG8_STAGE(PG8_SB(1, 1), cB + hstepB + kstep, voffB);
;     PG8_WAIT_V(6); PG8_BAR;
.LBB0_714:
	s_andn2_b64 vcc, exec, s[2:3]
	s_cbranch_vccnz .LBB0_751
	v_ashrrev_i32_e32 v2, 31, v0
	v_lshrrev_b32_e32 v2, 26, v2
	v_lshlrev_b32_e32 v1, 4, v0
	v_add_u32_e32 v2, v0, v2
	v_bfe_i32 v0, v0, 27, 1
	v_lshrrev_b32_e32 v0, 22, v0
	v_add_u32_e32 v0, v1, v0
	v_and_b32_e32 v0, 0xfffffc00, v0
	v_sub_u32_e32 v0, v1, v0
	v_ashrrev_i32_e32 v9, 6, v2
	v_lshrrev_b32_e32 v2, 4, v0
	v_bitop3_b32 v0, v2, v0, 32 bitop3:0x6c
	v_ashrrev_i32_e32 v3, 31, v0
	v_lshrrev_b32_e32 v3, 26, v3
	v_add_u32_e32 v3, v0, v3
	v_lshlrev_b32_e32 v2, 3, v9
	v_ashrrev_i32_e32 v10, 6, v3
	v_and_b32_e32 v3, 0xc0, v3
	v_and_b32_e32 v2, -16, v2
	v_sub_u32_e32 v0, v0, v3
	v_mov_b32_e32 v3, 1
	v_add_u32_e32 v2, v10, v2
	v_ashrrev_i16_sdwa v0, v3, sext(v0) dst_sel:DWORD dst_unused:UNUSED_PAD src0_sel:DWORD src1_sel:BYTE_0
	v_lshlrev_b32_e32 v4, 5, v9
	v_bfe_i32 v11, v0, 0, 16
	v_lshlrev_b32_e32 v0, 1, v2
	v_lshrrev_b32_e32 v5, 2, v2
	v_and_b32_e32 v6, 3, v10
	s_mov_b32 s3, 0x1fffe0
	v_and_b32_e32 v4, 32, v4
	v_and_b32_e32 v0, 24, v0
	v_and_b32_e32 v5, 4, v5
	v_and_or_b32 v6, v2, s3, v6
	v_or3_b32 v0, v6, v5, v0
	v_add_lshl_u32 v4, v4, v11, 1
	v_lshl_add_u32 v154, v0, 11, v4
	v_add_u32_e32 v0, 0x2000, v1
	v_ashrrev_i32_e32 v1, 31, v0
	v_lshrrev_b32_e32 v1, 22, v1
	v_add_u32_e32 v1, v0, v1
	v_ashrrev_i32_e32 v12, 10, v1
	v_mul_i32_i24_e32 v1, 0x400, v12
	v_sub_u32_e32 v0, v0, v1
	v_lshrrev_b32_e32 v1, 4, v0
	v_bitop3_b32 v0, v1, v0, 32 bitop3:0x6c
	v_lshl_add_u32 v152, v2, 11, v4
	v_ashrrev_i32_e32 v2, 31, v0
	v_lshrrev_b32_e32 v2, 26, v2
	s_add_u32 s38, s6, 0x19100000
	v_add_u32_e32 v2, v0, v2
	s_addc_u32 s39, s7, 0
	v_lshlrev_b32_e32 v1, 3, v12
	v_ashrrev_i32_e32 v13, 6, v2
	v_and_b32_e32 v2, 0xc0, v2
	s_add_u32 s40, s6, 0x4900000
	v_and_b32_e32 v1, -16, v1
	v_sub_u32_e32 v0, v0, v2
	s_addc_u32 s41, s7, 0
	s_ashr_i32 s2, s18, 6
	v_add_u32_e32 v1, v13, v1
	v_ashrrev_i16_sdwa v0, v3, sext(v0) dst_sel:DWORD dst_unused:UNUSED_PAD src0_sel:DWORD src1_sel:BYTE_0
	v_and_b32_e32 v3, 3, v13
	s_ashr_i32 s29, s28, 31
	s_ashr_i32 s9, s8, 31
	v_and_or_b32 v3, v1, s3, v3
	s_ashr_i32 s3, s18, 8
	s_lshl_b32 s42, s2, 10
	s_lshl_b64 s[4:5], s[28:29], 19
	s_lshl_b64 s[10:11], s[8:9], 19
	s_add_u32 s30, s40, s10
	v_lshlrev_b32_e32 v4, 5, v12
	v_bfe_i32 v14, v0, 0, 16
	v_lshlrev_b32_e32 v0, 1, v1
	v_lshrrev_b32_e32 v2, 2, v1
	s_addc_u32 s31, s41, s11
	s_add_i32 s43, s42, 0
	v_and_b32_e32 v4, 32, v4
	v_and_b32_e32 v0, 24, v0
	v_and_b32_e32 v2, 4, v2
	s_add_i32 m0, s43, 0x10000
	v_or3_b32 v0, v3, v2, v0
	v_add_lshl_u32 v2, v4, v14, 1
	global_load_lds_dwordx4 v154, s[30:31]
	s_add_i32 m0, s43, 0x12000
	v_lshl_add_u32 v158, v0, 11, v2
	s_add_u32 s10, s30, 0x40000
	global_load_lds_dwordx4 v158, s[30:31]
	s_addc_u32 s11, s31, 0
	s_add_i32 m0, s43, 0x14000
	v_lshl_add_u32 v156, v1, 11, v2
	global_load_lds_dwordx4 v154, s[10:11]
	s_add_i32 m0, s43, 0x16000
	s_add_u32 s34, s38, s4
	s_addc_u32 s35, s39, s5
	s_add_i32 s44, s43, 0x2000
	global_load_lds_dwordx4 v158, s[10:11]
	s_mov_b32 m0, s43
	s_add_u32 s4, s34, 0x40000
	global_load_lds_dwordx4 v152, s[34:35]
	s_mov_b32 m0, s44
	s_addc_u32 s5, s35, 0
	s_add_i32 s45, s43, 0x4000
	global_load_lds_dwordx4 v156, s[34:35]
	s_mov_b32 m0, s45
	s_add_i32 s46, s43, 0x6000
	global_load_lds_dwordx4 v152, s[4:5]
	s_mov_b32 m0, s46
	v_mov_b32_e32 v155, 0
	global_load_lds_dwordx4 v156, s[4:5]
	v_mov_b32_e32 v159, v155
	v_mov_b32_e32 v153, v155
	v_mov_b32_e32 v157, v155
	s_cmp_eq_u32 s3, 1
	s_mov_b32 s9, 0
	v_lshl_add_u64 v[6:7], s[30:31], 0, v[154:155]
	v_lshl_add_u64 v[4:5], s[30:31], 0, v[158:159]
	v_lshl_add_u64 v[0:1], s[34:35], 0, v[152:153]
	s_cselect_b64 s[10:11], -1, 0
	s_cmp_lg_u32 s3, 1
	v_lshl_add_u64 v[2:3], s[34:35], 0, v[156:157]
	s_cbranch_scc1 .LBB0_717
	s_barrier

; #define LAS __attribute__((address_space(3)))
; __device__ __forceinline__ unsigned xb_ld(unsigned* p)              { return __hip_atomic_load(p, __ATOMIC_RELAXED, __HIP_MEMORY_SCOPE_AGENT); }
; __device__ __forceinline__ unsigned xb_add(unsigned* p, unsigned v) { return __hip_atomic_fetch_add(p, v, __ATOMIC_RELAXED, __HIP_MEMORY_SCOPE_AGENT); }
; __device__ __forceinline__ unsigned xb_xcc_id() { return (unsigned)__builtin_amdgcn_s_getreg((3 << 11) | 20) & 0xFu; }
; #define XB_SPIN(cond, bar) do { unsigned _sp = 0; while (cond) { __builtin_amdgcn_s_sleep(1); \
;     if ((++_sp & 255u) == 0u) { if (xb_ld(&(bar)[XB_TMO])) break; if (_sp > XB_SPIN_CAP) { atomicAdd(&(bar)[XB_TMO], 1u); break; } } } } while (0)
; __device__ __forceinline__ bool is_leader(int wave_s) { int lane; asm volatile("v_mbcnt_lo_u32_b32 %0, -1, 0\n\tv_mbcnt_hi_u32_b32 %0, -1, %0" : "=v"(lane)); return wave_s == 0 && lane == 0; }
; __device__ __forceinline__ void grid_bar(unsigned* bar, volatile LAS unsigned* st, int wave_s, unsigned G) {
;     asm volatile("s_waitcnt vmcnt(0) lgkmcnt(0)" ::: "memory");
;     __syncthreads();
;     if (is_leader(wave_s)) {
;         const unsigned x = xb_xcc_id();
;         unsigned nloc = st[0], nx = st[1];
;         if (nloc == 0u) { xcd_barrier_complete(bar, x, G, nloc, nx); st[0] = nloc; st[1] = nx; }
;         const unsigned old = xb_add(&bar[XB_XSUB(x)], 1u);
;         const unsigned gen = old / nloc;
;         if (old + 1u == (gen + 1u) * nloc) {
;             __builtin_amdgcn_fence(__ATOMIC_RELEASE, "agent");
;             asm volatile("s_waitcnt vmcnt(0)" ::: "memory");
;             const unsigned og = xb_add(&bar[XB_TOP], 1u);
;             const unsigned tg = og / nx;
;             if (og + 1u == (tg + 1u) * nx) xb_add(&bar[XB_TOPGEN], 1u);
;             else XB_SPIN(xb_ld(&bar[XB_TOPGEN]) == tg, bar);
;             __builtin_amdgcn_fence(__ATOMIC_ACQUIRE, "agent");
;             xb_add(&bar[XB_XGEN(x)], 1u);
;             asm volatile("s_waitcnt vmcnt(0)" ::: "memory");
;         } else {
;             XB_SPIN(xb_ld(&bar[XB_XGEN(x)]) == gen, bar);
;             __builtin_amdgcn_fence(__ATOMIC_ACQUIRE, "agent");
;             asm volatile("s_waitcnt vmcnt(0)" ::: "memory");
;         }
;     }
;     __syncthreads();
; }
.LBB0_751:
	s_mov_b32 s2, s94
	s_mov_b32 s4, s95
	s_cmp_lt_i32 s2, 7
	s_cselect_b64 s[2:3], -1, 0
	s_cmp_gt_i32 s4, 6
	s_cselect_b64 s[4:5], -1, 0
	s_and_b64 s[2:3], s[2:3], s[4:5]
	s_andn2_b64 vcc, exec, s[2:3]
	s_cbranch_vccnz .LBB0_806
	s_mov_b32 s2, s94
	s_mov_b32 s4, s95
	s_cmp_lt_i32 s2, 8
	s_cselect_b64 s[2:3], -1, 0
	s_cmp_gt_i32 s4, 7
	s_cselect_b64 s[4:5], -1, 0
	s_and_b64 s[2:3], s[2:3], s[4:5]
	s_andn2_b64 vcc, exec, s[2:3]
	s_cbranch_vccnz .LBB0_806
	s_cmp_lt_u32 s79, 64
	s_waitcnt vmcnt(0) lgkmcnt(0)
	s_cselect_b64 s[2:3], -1, 0
	s_waitcnt vmcnt(0) lgkmcnt(0)
	s_barrier
	v_mbcnt_lo_u32_b32 v0, -1, 0
	v_mbcnt_hi_u32_b32 v0, -1, v0
	s_nop 0
	v_cmp_eq_u32_e32 vcc, 0, v0
	s_and_b64 s[4:5], s[2:3], vcc
	s_and_saveexec_b64 s[2:3], s[4:5]
	s_cbranch_execz .LBB0_805
	s_cmp_eq_u32 s98, 0
	s_cbranch_scc1 .Lgl_2
	s_load_dwordx2 s[4:5], s[0:1], 0xf0
	s_and_b32 s6, s78, 7
	s_lshl_b32 s6, s6, 8
	s_lshr_b32 s7, s92, 3
	s_mul_i32 s7, s7, 2
	v_mov_b32_e32 v0, s6
	v_mov_b32_e32 v1, 1
	s_waitcnt lgkmcnt(0)
	global_atomic_add v2, v0, v1, s[4:5] offset:1152 sc0
	buffer_inv sc1
	s_waitcnt vmcnt(0)
	v_readfirstlane_b32 s8, v2
	s_add_i32 s8, s8, 1
	s_cmp_eq_u32 s8, s7
	s_cbranch_scc0 .Lwt_2
	global_atomic_add v0, v1, s[4:5] offset:1216
	s_branch .Lac_2

; #define LAS __attribute__((address_space(3)))
; __device__ __forceinline__ unsigned xb_ld(unsigned* p)              { return __hip_atomic_load(p, __ATOMIC_RELAXED, __HIP_MEMORY_SCOPE_AGENT); }
; __device__ __forceinline__ unsigned xb_add(unsigned* p, unsigned v) { return __hip_atomic_fetch_add(p, v, __ATOMIC_RELAXED, __HIP_MEMORY_SCOPE_AGENT); }
; __device__ __forceinline__ unsigned xb_xcc_id() { return (unsigned)__builtin_amdgcn_s_getreg((3 << 11) | 20) & 0xFu; }
; #define XB_SPIN(cond, bar) do { unsigned _sp = 0; while (cond) { __builtin_amdgcn_s_sleep(1); \
;     if ((++_sp & 255u) == 0u) { if (xb_ld(&(bar)[XB_TMO])) break; if (_sp > XB_SPIN_CAP) { atomicAdd(&(bar)[XB_TMO], 1u); break; } } } } while (0)
; __device__ __forceinline__ bool is_leader(int wave_s) { int lane; asm volatile("v_mbcnt_lo_u32_b32 %0, -1, 0\n\tv_mbcnt_hi_u32_b32 %0, -1, %0" : "=v"(lane)); return wave_s == 0 && lane == 0; }
; __device__ __forceinline__ void grid_bar(unsigned* bar, volatile LAS unsigned* st, int wave_s, unsigned G) {
;     asm volatile("s_waitcnt vmcnt(0) lgkmcnt(0)" ::: "memory");
;     __syncthreads();
;     if (is_leader(wave_s)) {
;         const unsigned x = xb_xcc_id();
;         unsigned nloc = st[0], nx = st[1];
;         if (nloc == 0u) { xcd_barrier_complete(bar, x, G, nloc, nx); st[0] = nloc; st[1] = nx; }
;         const unsigned old = xb_add(&bar[XB_XSUB(x)], 1u);
;         const unsigned gen = old / nloc;
;         if (old + 1u == (gen + 1u) * nloc) {
;             __builtin_amdgcn_fence(__ATOMIC_RELEASE, "agent");
;             asm volatile("s_waitcnt vmcnt(0)" ::: "memory");
;             const unsigned og = xb_add(&bar[XB_TOP], 1u);
;             const unsigned tg = og / nx;
;             if (og + 1u == (tg + 1u) * nx) xb_add(&bar[XB_TOPGEN], 1u);
;             else XB_SPIN(xb_ld(&bar[XB_TOPGEN]) == tg, bar);
;             __builtin_amdgcn_fence(__ATOMIC_ACQUIRE, "agent");
;             xb_add(&bar[XB_XGEN(x)], 1u);
;             asm volatile("s_waitcnt vmcnt(0)" ::: "memory");
;         } else {
;             XB_SPIN(xb_ld(&bar[XB_XGEN(x)]) == gen, bar);
;             __builtin_amdgcn_fence(__ATOMIC_ACQUIRE, "agent");
;             asm volatile("s_waitcnt vmcnt(0)" ::: "memory");
;         }
;     }
;     __syncthreads();
; }
.LBB0_826:
	s_mov_b32 s2, s94
	s_mov_b32 s4, s95
	s_cmp_lt_i32 s2, 8
	s_cselect_b64 s[2:3], -1, 0
	s_cmp_gt_i32 s4, 7
	s_cselect_b64 s[4:5], -1, 0
	s_and_b64 s[2:3], s[2:3], s[4:5]
	s_andn2_b64 vcc, exec, s[2:3]
	s_cbranch_vccnz .LBB0_881
	s_mov_b32 s2, s94
	s_mov_b32 s4, s95
	s_cmp_lt_i32 s2, 9
	s_cselect_b64 s[2:3], -1, 0
	s_cmp_gt_i32 s4, 8
	s_cselect_b64 s[4:5], -1, 0
	s_and_b64 s[2:3], s[2:3], s[4:5]
	s_andn2_b64 vcc, exec, s[2:3]
	s_cbranch_vccnz .LBB0_881
	s_cmp_lt_u32 s79, 64
	s_waitcnt vmcnt(0) lgkmcnt(0)
	s_cselect_b64 s[2:3], -1, 0
	s_waitcnt vmcnt(0) lgkmcnt(0)
	s_barrier
	v_mbcnt_lo_u32_b32 v0, -1, 0
	v_mbcnt_hi_u32_b32 v0, -1, v0
	s_nop 0
	v_cmp_eq_u32_e32 vcc, 0, v0
	s_and_b64 s[4:5], s[2:3], vcc
	s_and_saveexec_b64 s[2:3], s[4:5]
	s_cbranch_execz .LBB0_880
	s_cmp_eq_u32 s98, 0
	s_cbranch_scc1 .Lgl_3
	s_load_dwordx2 s[4:5], s[0:1], 0xf0
	s_and_b32 s6, s78, 7
	s_lshl_b32 s6, s6, 8
	s_lshr_b32 s7, s92, 3
	s_mul_i32 s7, s7, 3
	v_mov_b32_e32 v0, s6
	v_mov_b32_e32 v1, 1
	s_waitcnt lgkmcnt(0)
	global_atomic_add v2, v0, v1, s[4:5] offset:1152 sc0
	buffer_inv sc1
	s_waitcnt vmcnt(0)
	v_readfirstlane_b32 s8, v2
	s_add_i32 s8, s8, 1
	s_cmp_eq_u32 s8, s7
	s_cbranch_scc0 .Lwt_3
	global_atomic_add v0, v1, s[4:5] offset:1216
	s_branch .Lac_3

; #define LAS __attribute__((address_space(3)))
; __device__ __forceinline__ unsigned xb_ld(unsigned* p)              { return __hip_atomic_load(p, __ATOMIC_RELAXED, __HIP_MEMORY_SCOPE_AGENT); }
; __device__ __forceinline__ unsigned xb_add(unsigned* p, unsigned v) { return __hip_atomic_fetch_add(p, v, __ATOMIC_RELAXED, __HIP_MEMORY_SCOPE_AGENT); }
; __device__ __forceinline__ unsigned xb_xcc_id() { return (unsigned)__builtin_amdgcn_s_getreg((3 << 11) | 20) & 0xFu; }
; #define XB_SPIN(cond, bar) do { unsigned _sp = 0; while (cond) { __builtin_amdgcn_s_sleep(1); \
;     if ((++_sp & 255u) == 0u) { if (xb_ld(&(bar)[XB_TMO])) break; if (_sp > XB_SPIN_CAP) { atomicAdd(&(bar)[XB_TMO], 1u); break; } } } } while (0)
; __device__ __forceinline__ bool is_leader(int wave_s) { int lane; asm volatile("v_mbcnt_lo_u32_b32 %0, -1, 0\n\tv_mbcnt_hi_u32_b32 %0, -1, %0" : "=v"(lane)); return wave_s == 0 && lane == 0; }
; __device__ __forceinline__ void grid_bar(unsigned* bar, volatile LAS unsigned* st, int wave_s, unsigned G) {
;     asm volatile("s_waitcnt vmcnt(0) lgkmcnt(0)" ::: "memory");
;     __syncthreads();
;     if (is_leader(wave_s)) {
;         const unsigned x = xb_xcc_id();
;         unsigned nloc = st[0], nx = st[1];
;         if (nloc == 0u) { xcd_barrier_complete(bar, x, G, nloc, nx); st[0] = nloc; st[1] = nx; }
;         const unsigned old = xb_add(&bar[XB_XSUB(x)], 1u);
;         const unsigned gen = old / nloc;
;         if (old + 1u == (gen + 1u) * nloc) {
;             __builtin_amdgcn_fence(__ATOMIC_RELEASE, "agent");
;             asm volatile("s_waitcnt vmcnt(0)" ::: "memory");
;             const unsigned og = xb_add(&bar[XB_TOP], 1u);
;             const unsigned tg = og / nx;
;             if (og + 1u == (tg + 1u) * nx) xb_add(&bar[XB_TOPGEN], 1u);
;             else XB_SPIN(xb_ld(&bar[XB_TOPGEN]) == tg, bar);
;             __builtin_amdgcn_fence(__ATOMIC_ACQUIRE, "agent");
;             xb_add(&bar[XB_XGEN(x)], 1u);
;             asm volatile("s_waitcnt vmcnt(0)" ::: "memory");
;         } else {
;             XB_SPIN(xb_ld(&bar[XB_XGEN(x)]) == gen, bar);
;             __builtin_amdgcn_fence(__ATOMIC_ACQUIRE, "agent");
;             asm volatile("s_waitcnt vmcnt(0)" ::: "memory");
;         }
;     }
;     __syncthreads();
; }
.LBB0_956:
	s_mov_b32 s2, s94
	s_mov_b32 s4, s95
	s_cmp_lt_i32 s2, 9
	s_cselect_b64 s[2:3], -1, 0
	s_cmp_gt_i32 s4, 8
	s_cselect_b64 s[4:5], -1, 0
	s_and_b64 s[2:3], s[2:3], s[4:5]
	s_andn2_b64 vcc, exec, s[2:3]
	s_cbranch_vccnz .LBB0_1011
	s_mov_b32 s2, s94
	s_mov_b32 s4, s95
	s_cmp_lt_i32 s2, 10
	s_cselect_b64 s[2:3], -1, 0
	s_cmp_gt_i32 s4, 9
	s_cselect_b64 s[4:5], -1, 0
	s_and_b64 s[2:3], s[2:3], s[4:5]
	s_andn2_b64 vcc, exec, s[2:3]
	s_cbranch_vccnz .LBB0_1011
	s_cmp_lt_u32 s79, 64
	s_waitcnt vmcnt(0) lgkmcnt(0)
	s_cselect_b64 s[2:3], -1, 0
	s_waitcnt vmcnt(0) lgkmcnt(0)
	s_barrier
	v_mbcnt_lo_u32_b32 v0, -1, 0
	v_mbcnt_hi_u32_b32 v0, -1, v0
	s_nop 0
	v_cmp_eq_u32_e32 vcc, 0, v0
	s_and_b64 s[4:5], s[2:3], vcc
	s_and_saveexec_b64 s[2:3], s[4:5]
	s_cbranch_execz .LBB0_1010
	s_cmp_eq_u32 s98, 0
	s_cbranch_scc1 .Lgl_4
	s_load_dwordx2 s[4:5], s[0:1], 0xf0
	s_and_b32 s6, s78, 7
	s_lshl_b32 s6, s6, 8
	s_lshr_b32 s7, s92, 3
	s_mul_i32 s7, s7, 4
	v_mov_b32_e32 v0, s6
	v_mov_b32_e32 v1, 1
	s_waitcnt lgkmcnt(0)
	global_atomic_add v2, v0, v1, s[4:5] offset:1152 sc0
	buffer_inv sc1
	s_waitcnt vmcnt(0)
	v_readfirstlane_b32 s8, v2
	s_add_i32 s8, s8, 1
	s_cmp_eq_u32 s8, s7
	s_cbranch_scc0 .Lwt_4
	global_atomic_add v0, v1, s[4:5] offset:1216
	s_branch .Lac_4

; #define LAS __attribute__((address_space(3)))
; __device__ __forceinline__ unsigned xb_ld(unsigned* p)              { return __hip_atomic_load(p, __ATOMIC_RELAXED, __HIP_MEMORY_SCOPE_AGENT); }
; __device__ __forceinline__ unsigned xb_add(unsigned* p, unsigned v) { return __hip_atomic_fetch_add(p, v, __ATOMIC_RELAXED, __HIP_MEMORY_SCOPE_AGENT); }
; __device__ __forceinline__ unsigned xb_xcc_id() { return (unsigned)__builtin_amdgcn_s_getreg((3 << 11) | 20) & 0xFu; }
; #define XB_SPIN(cond, bar) do { unsigned _sp = 0; while (cond) { __builtin_amdgcn_s_sleep(1); \
;     if ((++_sp & 255u) == 0u) { if (xb_ld(&(bar)[XB_TMO])) break; if (_sp > XB_SPIN_CAP) { atomicAdd(&(bar)[XB_TMO], 1u); break; } } } } while (0)
; __device__ __forceinline__ bool is_leader(int wave_s) { int lane; asm volatile("v_mbcnt_lo_u32_b32 %0, -1, 0\n\tv_mbcnt_hi_u32_b32 %0, -1, %0" : "=v"(lane)); return wave_s == 0 && lane == 0; }
; __device__ __forceinline__ void grid_bar(unsigned* bar, volatile LAS unsigned* st, int wave_s, unsigned G) {
;     asm volatile("s_waitcnt vmcnt(0) lgkmcnt(0)" ::: "memory");
;     __syncthreads();
;     if (is_leader(wave_s)) {
;         const unsigned x = xb_xcc_id();
;         unsigned nloc = st[0], nx = st[1];
;         if (nloc == 0u) { xcd_barrier_complete(bar, x, G, nloc, nx); st[0] = nloc; st[1] = nx; }
;         const unsigned old = xb_add(&bar[XB_XSUB(x)], 1u);
;         const unsigned gen = old / nloc;
;         if (old + 1u == (gen + 1u) * nloc) {
;             __builtin_amdgcn_fence(__ATOMIC_RELEASE, "agent");
;             asm volatile("s_waitcnt vmcnt(0)" ::: "memory");
;             const unsigned og = xb_add(&bar[XB_TOP], 1u);
;             const unsigned tg = og / nx;
;             if (og + 1u == (tg + 1u) * nx) xb_add(&bar[XB_TOPGEN], 1u);
;             else XB_SPIN(xb_ld(&bar[XB_TOPGEN]) == tg, bar);
;             __builtin_amdgcn_fence(__ATOMIC_ACQUIRE, "agent");
;             xb_add(&bar[XB_XGEN(x)], 1u);
;             asm volatile("s_waitcnt vmcnt(0)" ::: "memory");
;         } else {
;             XB_SPIN(xb_ld(&bar[XB_XGEN(x)]) == gen, bar);
;             __builtin_amdgcn_fence(__ATOMIC_ACQUIRE, "agent");
;             asm volatile("s_waitcnt vmcnt(0)" ::: "memory");
;         }
;     }
;     __syncthreads();
; }
.LBB0_1057:
	s_mov_b32 s2, s94
	s_mov_b32 s4, s95
	s_cmp_lt_i32 s2, 10
	s_cselect_b64 s[2:3], -1, 0
	s_cmp_gt_i32 s4, 9
	s_cselect_b64 s[4:5], -1, 0
	s_and_b64 s[2:3], s[2:3], s[4:5]
	s_andn2_b64 vcc, exec, s[2:3]
	s_cbranch_vccnz .LBB0_1112
	s_mov_b32 s2, s94
	s_mov_b32 s4, s95
	s_cmp_lt_i32 s2, 11
	s_cselect_b64 s[2:3], -1, 0
	s_cmp_gt_i32 s4, 10
	s_cselect_b64 s[4:5], -1, 0
	s_and_b64 s[2:3], s[2:3], s[4:5]
	s_andn2_b64 vcc, exec, s[2:3]
	s_cbranch_vccnz .LBB0_1112
	s_cmp_lt_u32 s79, 64
	s_waitcnt vmcnt(0) lgkmcnt(0)
	s_cselect_b64 s[2:3], -1, 0
	s_waitcnt vmcnt(0) lgkmcnt(0)
	s_barrier
	v_mbcnt_lo_u32_b32 v0, -1, 0
	v_mbcnt_hi_u32_b32 v0, -1, v0
	s_nop 0
	v_cmp_eq_u32_e32 vcc, 0, v0
	s_and_b64 s[4:5], s[2:3], vcc
	s_and_saveexec_b64 s[2:3], s[4:5]
	s_cbranch_execz .LBB0_1111
	s_cmp_eq_u32 s98, 0
	s_cbranch_scc1 .Lgl_5
	s_load_dwordx2 s[4:5], s[0:1], 0xf0
	s_and_b32 s6, s78, 7
	s_lshl_b32 s6, s6, 8
	s_lshr_b32 s7, s92, 3
	s_mul_i32 s7, s7, 5
	v_mov_b32_e32 v0, s6
	v_mov_b32_e32 v1, 1
	s_waitcnt lgkmcnt(0)
	global_atomic_add v2, v0, v1, s[4:5] offset:1152 sc0
	buffer_inv sc1
	s_waitcnt vmcnt(0)
	v_readfirstlane_b32 s8, v2
	s_add_i32 s8, s8, 1
	s_cmp_eq_u32 s8, s7
	s_cbranch_scc0 .Lwt_5
	global_atomic_add v0, v1, s[4:5] offset:1216
	s_branch .Lac_5

; #define LAS __attribute__((address_space(3)))
; __device__ __forceinline__ unsigned xb_ld(unsigned* p)              { return __hip_atomic_load(p, __ATOMIC_RELAXED, __HIP_MEMORY_SCOPE_AGENT); }
; __device__ __forceinline__ unsigned xb_add(unsigned* p, unsigned v) { return __hip_atomic_fetch_add(p, v, __ATOMIC_RELAXED, __HIP_MEMORY_SCOPE_AGENT); }
; __device__ __forceinline__ unsigned xb_xcc_id() { return (unsigned)__builtin_amdgcn_s_getreg((3 << 11) | 20) & 0xFu; }
; #define XB_SPIN(cond, bar) do { unsigned _sp = 0; while (cond) { __builtin_amdgcn_s_sleep(1); \
;     if ((++_sp & 255u) == 0u) { if (xb_ld(&(bar)[XB_TMO])) break; if (_sp > XB_SPIN_CAP) { atomicAdd(&(bar)[XB_TMO], 1u); break; } } } } while (0)
; __device__ __forceinline__ bool is_leader(int wave_s) { int lane; asm volatile("v_mbcnt_lo_u32_b32 %0, -1, 0\n\tv_mbcnt_hi_u32_b32 %0, -1, %0" : "=v"(lane)); return wave_s == 0 && lane == 0; }
; __device__ __forceinline__ void grid_bar(unsigned* bar, volatile LAS unsigned* st, int wave_s, unsigned G) {
;     asm volatile("s_waitcnt vmcnt(0) lgkmcnt(0)" ::: "memory");
;     __syncthreads();
;     if (is_leader(wave_s)) {
;         const unsigned x = xb_xcc_id();
;         unsigned nloc = st[0], nx = st[1];
;         if (nloc == 0u) { xcd_barrier_complete(bar, x, G, nloc, nx); st[0] = nloc; st[1] = nx; }
;         const unsigned old = xb_add(&bar[XB_XSUB(x)], 1u);
;         const unsigned gen = old / nloc;
;         if (old + 1u == (gen + 1u) * nloc) {
;             __builtin_amdgcn_fence(__ATOMIC_RELEASE, "agent");
;             asm volatile("s_waitcnt vmcnt(0)" ::: "memory");
;             const unsigned og = xb_add(&bar[XB_TOP], 1u);
;             const unsigned tg = og / nx;
;             if (og + 1u == (tg + 1u) * nx) xb_add(&bar[XB_TOPGEN], 1u);
;             else XB_SPIN(xb_ld(&bar[XB_TOPGEN]) == tg, bar);
;             __builtin_amdgcn_fence(__ATOMIC_ACQUIRE, "agent");
;             xb_add(&bar[XB_XGEN(x)], 1u);
;             asm volatile("s_waitcnt vmcnt(0)" ::: "memory");
;         } else {
;             XB_SPIN(xb_ld(&bar[XB_XGEN(x)]) == gen, bar);
;             __builtin_amdgcn_fence(__ATOMIC_ACQUIRE, "agent");
;             asm volatile("s_waitcnt vmcnt(0)" ::: "memory");
;         }
;     }
;     __syncthreads();
; }
.LBB0_1132:
	s_mov_b32 s4, s95
	s_mov_b32 s2, s94
	s_cmp_lt_i32 s2, 11
	s_cselect_b64 s[2:3], -1, 0
	s_cmp_gt_i32 s4, 10
	s_cselect_b64 s[4:5], -1, 0
	s_and_b64 s[2:3], s[2:3], s[4:5]
	s_andn2_b64 vcc, exec, s[2:3]
	s_cbranch_vccnz .LBB0_1187
	s_mov_b32 s4, s95
	s_mov_b32 s2, s94
	s_cmp_lt_i32 s2, 12
	s_cselect_b64 s[2:3], -1, 0
	s_cmp_gt_i32 s4, 11
	s_cselect_b64 s[4:5], -1, 0
	s_and_b64 s[2:3], s[2:3], s[4:5]
	s_andn2_b64 vcc, exec, s[2:3]
	s_cbranch_vccnz .LBB0_1187
	s_cmp_lt_u32 s79, 64
	s_waitcnt vmcnt(0) lgkmcnt(0)
	s_cselect_b64 s[2:3], -1, 0
	s_waitcnt vmcnt(0) lgkmcnt(0)
	s_barrier
	v_mbcnt_lo_u32_b32 v0, -1, 0
	v_mbcnt_hi_u32_b32 v0, -1, v0
	s_nop 0
	v_cmp_eq_u32_e32 vcc, 0, v0
	s_and_b64 s[4:5], s[2:3], vcc
	s_and_saveexec_b64 s[2:3], s[4:5]
	s_cbranch_execz .LBB0_1186
	s_cmp_eq_u32 s98, 0
	s_cbranch_scc1 .Lgl_6
	s_load_dwordx2 s[4:5], s[0:1], 0xf0
	s_and_b32 s6, s78, 7
	s_lshl_b32 s6, s6, 8
	s_lshr_b32 s7, s92, 3
	s_mul_i32 s7, s7, 6
	v_mov_b32_e32 v0, s6
	v_mov_b32_e32 v1, 1
	s_waitcnt lgkmcnt(0)
	global_atomic_add v2, v0, v1, s[4:5] offset:1152 sc0
	buffer_inv sc1
	s_waitcnt vmcnt(0)
	v_readfirstlane_b32 s8, v2
	s_add_i32 s8, s8, 1
	s_cmp_eq_u32 s8, s7
	s_cbranch_scc0 .Lwt_6
	global_atomic_add v0, v1, s[4:5] offset:1216
	s_branch .Lac_6

; #define LAS __attribute__((address_space(3)))
; __device__ __forceinline__ unsigned xb_ld(unsigned* p)              { return __hip_atomic_load(p, __ATOMIC_RELAXED, __HIP_MEMORY_SCOPE_AGENT); }
; __device__ __forceinline__ unsigned xb_add(unsigned* p, unsigned v) { return __hip_atomic_fetch_add(p, v, __ATOMIC_RELAXED, __HIP_MEMORY_SCOPE_AGENT); }
; __device__ __forceinline__ unsigned xb_xcc_id() { return (unsigned)__builtin_amdgcn_s_getreg((3 << 11) | 20) & 0xFu; }
; #define XB_SPIN(cond, bar) do { unsigned _sp = 0; while (cond) { __builtin_amdgcn_s_sleep(1); \
;     if ((++_sp & 255u) == 0u) { if (xb_ld(&(bar)[XB_TMO])) break; if (_sp > XB_SPIN_CAP) { atomicAdd(&(bar)[XB_TMO], 1u); break; } } } } while (0)
; __device__ __forceinline__ bool is_leader(int wave_s) { int lane; asm volatile("v_mbcnt_lo_u32_b32 %0, -1, 0\n\tv_mbcnt_hi_u32_b32 %0, -1, %0" : "=v"(lane)); return wave_s == 0 && lane == 0; }
; __device__ __forceinline__ void grid_bar(unsigned* bar, volatile LAS unsigned* st, int wave_s, unsigned G) {
;     asm volatile("s_waitcnt vmcnt(0) lgkmcnt(0)" ::: "memory");
;     __syncthreads();
;     if (is_leader(wave_s)) {
;         const unsigned x = xb_xcc_id();
;         unsigned nloc = st[0], nx = st[1];
;         if (nloc == 0u) { xcd_barrier_complete(bar, x, G, nloc, nx); st[0] = nloc; st[1] = nx; }
;         const unsigned old = xb_add(&bar[XB_XSUB(x)], 1u);
;         const unsigned gen = old / nloc;
;         if (old + 1u == (gen + 1u) * nloc) {
;             __builtin_amdgcn_fence(__ATOMIC_RELEASE, "agent");
;             asm volatile("s_waitcnt vmcnt(0)" ::: "memory");
;             const unsigned og = xb_add(&bar[XB_TOP], 1u);
;             const unsigned tg = og / nx;
;             if (og + 1u == (tg + 1u) * nx) xb_add(&bar[XB_TOPGEN], 1u);
;             else XB_SPIN(xb_ld(&bar[XB_TOPGEN]) == tg, bar);
;             __builtin_amdgcn_fence(__ATOMIC_ACQUIRE, "agent");
;             xb_add(&bar[XB_XGEN(x)], 1u);
;             asm volatile("s_waitcnt vmcnt(0)" ::: "memory");
;         } else {
;             XB_SPIN(xb_ld(&bar[XB_XGEN(x)]) == gen, bar);
;             __builtin_amdgcn_fence(__ATOMIC_ACQUIRE, "agent");
;             asm volatile("s_waitcnt vmcnt(0)" ::: "memory");
;         }
;     }
;     __syncthreads();
; }
.LBB0_1236:
	s_mov_b32 s2, s94
	s_mov_b32 s4, s95
	s_cmp_lt_i32 s2, 12
	s_cselect_b64 s[2:3], -1, 0
	s_cmp_gt_i32 s4, 11
	s_cselect_b64 s[4:5], -1, 0
	s_and_b64 s[2:3], s[2:3], s[4:5]
	s_andn2_b64 vcc, exec, s[2:3]
	s_cbranch_vccnz .LBB0_1291
	s_mov_b32 s2, s94
	s_mov_b32 s4, s95
	s_cmp_lt_i32 s2, 13
	s_cselect_b64 s[2:3], -1, 0
	s_cmp_gt_i32 s4, 12
	s_cselect_b64 s[4:5], -1, 0
	s_and_b64 s[2:3], s[2:3], s[4:5]
	s_andn2_b64 vcc, exec, s[2:3]
	s_cbranch_vccnz .LBB0_1291
	s_cmp_lt_u32 s79, 64
	s_waitcnt vmcnt(0) lgkmcnt(0)
	s_cselect_b64 s[2:3], -1, 0
	s_waitcnt vmcnt(0) lgkmcnt(0)
	s_barrier
	v_mbcnt_lo_u32_b32 v0, -1, 0
	v_mbcnt_hi_u32_b32 v0, -1, v0
	s_nop 0
	v_cmp_eq_u32_e32 vcc, 0, v0
	s_and_b64 s[4:5], s[2:3], vcc
	s_and_saveexec_b64 s[2:3], s[4:5]
	s_cbranch_execz .LBB0_1290
	s_cmp_eq_u32 s98, 0
	s_cbranch_scc1 .Lgl_7
	s_load_dwordx2 s[4:5], s[0:1], 0xf0
	s_and_b32 s6, s78, 7
	s_lshl_b32 s6, s6, 8
	s_lshr_b32 s7, s92, 3
	s_mul_i32 s7, s7, 7
	v_mov_b32_e32 v0, s6
	v_mov_b32_e32 v1, 1
	s_waitcnt lgkmcnt(0)
	global_atomic_add v2, v0, v1, s[4:5] offset:1152 sc0
	buffer_inv sc1
	s_waitcnt vmcnt(0)
	v_readfirstlane_b32 s8, v2
	s_add_i32 s8, s8, 1
	s_cmp_eq_u32 s8, s7
	s_cbranch_scc0 .Lwt_7
	global_atomic_add v0, v1, s[4:5] offset:1216
	s_branch .Lac_7

; #define LAS __attribute__((address_space(3)))
; __device__ __forceinline__ unsigned xb_ld(unsigned* p)              { return __hip_atomic_load(p, __ATOMIC_RELAXED, __HIP_MEMORY_SCOPE_AGENT); }
; __device__ __forceinline__ unsigned xb_add(unsigned* p, unsigned v) { return __hip_atomic_fetch_add(p, v, __ATOMIC_RELAXED, __HIP_MEMORY_SCOPE_AGENT); }
; __device__ __forceinline__ unsigned xb_xcc_id() { return (unsigned)__builtin_amdgcn_s_getreg((3 << 11) | 20) & 0xFu; }
; #define XB_SPIN(cond, bar) do { unsigned _sp = 0; while (cond) { __builtin_amdgcn_s_sleep(1); \
;     if ((++_sp & 255u) == 0u) { if (xb_ld(&(bar)[XB_TMO])) break; if (_sp > XB_SPIN_CAP) { atomicAdd(&(bar)[XB_TMO], 1u); break; } } } } while (0)
; __device__ __forceinline__ bool is_leader(int wave_s) { int lane; asm volatile("v_mbcnt_lo_u32_b32 %0, -1, 0\n\tv_mbcnt_hi_u32_b32 %0, -1, %0" : "=v"(lane)); return wave_s == 0 && lane == 0; }
; __device__ __forceinline__ void grid_bar(unsigned* bar, volatile LAS unsigned* st, int wave_s, unsigned G) {
;     asm volatile("s_waitcnt vmcnt(0) lgkmcnt(0)" ::: "memory");
;     __syncthreads();
;     if (is_leader(wave_s)) {
;         const unsigned x = xb_xcc_id();
;         unsigned nloc = st[0], nx = st[1];
;         if (nloc == 0u) { xcd_barrier_complete(bar, x, G, nloc, nx); st[0] = nloc; st[1] = nx; }
;         const unsigned old = xb_add(&bar[XB_XSUB(x)], 1u);
;         const unsigned gen = old / nloc;
;         if (old + 1u == (gen + 1u) * nloc) {
;             __builtin_amdgcn_fence(__ATOMIC_RELEASE, "agent");
;             asm volatile("s_waitcnt vmcnt(0)" ::: "memory");
;             const unsigned og = xb_add(&bar[XB_TOP], 1u);
;             const unsigned tg = og / nx;
;             if (og + 1u == (tg + 1u) * nx) xb_add(&bar[XB_TOPGEN], 1u);
;             else XB_SPIN(xb_ld(&bar[XB_TOPGEN]) == tg, bar);
;             __builtin_amdgcn_fence(__ATOMIC_ACQUIRE, "agent");
;             xb_add(&bar[XB_XGEN(x)], 1u);
;             asm volatile("s_waitcnt vmcnt(0)" ::: "memory");
;         } else {
;             XB_SPIN(xb_ld(&bar[XB_XGEN(x)]) == gen, bar);
;             __builtin_amdgcn_fence(__ATOMIC_ACQUIRE, "agent");
;             asm volatile("s_waitcnt vmcnt(0)" ::: "memory");
;         }
;     }
;     __syncthreads();
; }
.LBB0_1532:
	s_mov_b32 s2, s94
	s_mov_b32 s4, s95
	s_cmp_lt_i32 s2, 15
	s_cselect_b64 s[2:3], -1, 0
	s_cmp_gt_i32 s4, 14
	s_cselect_b64 s[4:5], -1, 0
	s_and_b64 s[2:3], s[2:3], s[4:5]
	s_andn2_b64 vcc, exec, s[2:3]
	s_cbranch_vccnz .LBB0_1587
	s_mov_b32 s2, s94
	s_mov_b32 s4, s95
	s_cmp_lt_i32 s2, 16
	s_cselect_b64 s[2:3], -1, 0
	s_cmp_gt_i32 s4, 15
	s_cselect_b64 s[4:5], -1, 0
	s_and_b64 s[2:3], s[2:3], s[4:5]
	s_andn2_b64 vcc, exec, s[2:3]
	s_cbranch_vccnz .LBB0_1587
	s_cmp_lt_u32 s79, 64
	s_waitcnt vmcnt(0) lgkmcnt(0)
	s_cselect_b64 s[2:3], -1, 0
	s_waitcnt vmcnt(0) lgkmcnt(0)
	s_barrier
	v_mbcnt_lo_u32_b32 v0, -1, 0
	v_mbcnt_hi_u32_b32 v0, -1, v0
	s_nop 0
	v_cmp_eq_u32_e32 vcc, 0, v0
	s_and_b64 s[4:5], s[2:3], vcc
	s_and_saveexec_b64 s[2:3], s[4:5]
	s_cbranch_execz .LBB0_1586
	s_cmp_eq_u32 s98, 0
	s_cbranch_scc1 .Lgl_8
	s_load_dwordx2 s[4:5], s[0:1], 0xf0
	s_and_b32 s6, s78, 7
	s_lshl_b32 s6, s6, 8
	s_lshr_b32 s7, s92, 3
	s_mul_i32 s7, s7, 8
	v_mov_b32_e32 v0, s6
	v_mov_b32_e32 v1, 1
	s_waitcnt lgkmcnt(0)
	global_atomic_add v2, v0, v1, s[4:5] offset:1152 sc0
	buffer_inv sc1
	s_waitcnt vmcnt(0)
	v_readfirstlane_b32 s8, v2
	s_add_i32 s8, s8, 1
	s_cmp_eq_u32 s8, s7
	s_cbranch_scc0 .Lwt_8
	global_atomic_add v0, v1, s[4:5] offset:1216
	s_branch .Lac_8

; #define LAS __attribute__((address_space(3)))
; __device__ __forceinline__ unsigned xb_ld(unsigned* p)              { return __hip_atomic_load(p, __ATOMIC_RELAXED, __HIP_MEMORY_SCOPE_AGENT); }
; __device__ __forceinline__ unsigned xb_add(unsigned* p, unsigned v) { return __hip_atomic_fetch_add(p, v, __ATOMIC_RELAXED, __HIP_MEMORY_SCOPE_AGENT); }
; __device__ __forceinline__ unsigned xb_xcc_id() { return (unsigned)__builtin_amdgcn_s_getreg((3 << 11) | 20) & 0xFu; }
; #define XB_SPIN(cond, bar) do { unsigned _sp = 0; while (cond) { __builtin_amdgcn_s_sleep(1); \
;     if ((++_sp & 255u) == 0u) { if (xb_ld(&(bar)[XB_TMO])) break; if (_sp > XB_SPIN_CAP) { atomicAdd(&(bar)[XB_TMO], 1u); break; } } } } while (0)
; __device__ __forceinline__ bool is_leader(int wave_s) { int lane; asm volatile("v_mbcnt_lo_u32_b32 %0, -1, 0\n\tv_mbcnt_hi_u32_b32 %0, -1, %0" : "=v"(lane)); return wave_s == 0 && lane == 0; }
; __device__ __forceinline__ void grid_bar(unsigned* bar, volatile LAS unsigned* st, int wave_s, unsigned G) {
;     asm volatile("s_waitcnt vmcnt(0) lgkmcnt(0)" ::: "memory");
;     __syncthreads();
;     if (is_leader(wave_s)) {
;         const unsigned x = xb_xcc_id();
;         unsigned nloc = st[0], nx = st[1];
;         if (nloc == 0u) { xcd_barrier_complete(bar, x, G, nloc, nx); st[0] = nloc; st[1] = nx; }
;         const unsigned old = xb_add(&bar[XB_XSUB(x)], 1u);
;         const unsigned gen = old / nloc;
;         if (old + 1u == (gen + 1u) * nloc) {
;             __builtin_amdgcn_fence(__ATOMIC_RELEASE, "agent");
;             asm volatile("s_waitcnt vmcnt(0)" ::: "memory");
;             const unsigned og = xb_add(&bar[XB_TOP], 1u);
;             const unsigned tg = og / nx;
;             if (og + 1u == (tg + 1u) * nx) xb_add(&bar[XB_TOPGEN], 1u);
;             else XB_SPIN(xb_ld(&bar[XB_TOPGEN]) == tg, bar);
;             __builtin_amdgcn_fence(__ATOMIC_ACQUIRE, "agent");
;             xb_add(&bar[XB_XGEN(x)], 1u);
;             asm volatile("s_waitcnt vmcnt(0)" ::: "memory");
;         } else {
;             XB_SPIN(xb_ld(&bar[XB_XGEN(x)]) == gen, bar);
;             __builtin_amdgcn_fence(__ATOMIC_ACQUIRE, "agent");
;             asm volatile("s_waitcnt vmcnt(0)" ::: "memory");
;         }
;     }
;     __syncthreads();
; }
.LBB0_1658:
	s_mov_b32 s2, s94
	s_mov_b32 s4, s95
	s_cmp_lt_i32 s2, 17
	s_cselect_b64 s[2:3], -1, 0
	s_cmp_gt_i32 s4, 16
	s_cselect_b64 s[4:5], -1, 0
	s_and_b64 s[2:3], s[2:3], s[4:5]
	s_andn2_b64 vcc, exec, s[2:3]
	s_cbranch_vccnz .LBB0_1713
	s_mov_b32 s2, s94
	s_mov_b32 s4, s95
	s_cmp_lt_i32 s2, 18
	s_cselect_b64 s[2:3], -1, 0
	s_cmp_gt_i32 s4, 17
	s_cselect_b64 s[4:5], -1, 0
	s_and_b64 s[2:3], s[2:3], s[4:5]
	s_andn2_b64 vcc, exec, s[2:3]
	s_cbranch_vccnz .LBB0_1713
	s_cmp_lt_u32 s79, 64
	s_waitcnt vmcnt(0) lgkmcnt(0)
	s_cselect_b64 s[2:3], -1, 0
	s_waitcnt vmcnt(0) lgkmcnt(0)
	s_barrier
	v_mbcnt_lo_u32_b32 v0, -1, 0
	v_mbcnt_hi_u32_b32 v0, -1, v0
	s_nop 0
	v_cmp_eq_u32_e32 vcc, 0, v0
	s_and_b64 s[4:5], s[2:3], vcc
	s_and_saveexec_b64 s[2:3], s[4:5]
	s_cbranch_execz .LBB0_1712
	s_cmp_eq_u32 s98, 0
	s_cbranch_scc1 .Lgl_9
	s_load_dwordx2 s[4:5], s[0:1], 0xf0
	s_and_b32 s6, s78, 7
	s_lshl_b32 s6, s6, 8
	s_lshr_b32 s7, s92, 3
	s_mul_i32 s7, s7, 9
	v_mov_b32_e32 v0, s6
	v_mov_b32_e32 v1, 1
	s_waitcnt lgkmcnt(0)
	global_atomic_add v2, v0, v1, s[4:5] offset:1152 sc0
	buffer_inv sc1
	s_waitcnt vmcnt(0)
	v_readfirstlane_b32 s8, v2
	s_add_i32 s8, s8, 1
	s_cmp_eq_u32 s8, s7
	s_cbranch_scc0 .Lwt_9
	global_atomic_add v0, v1, s[4:5] offset:1216
	s_branch .Lac_9

; #define LAS __attribute__((address_space(3)))
; __device__ __forceinline__ unsigned xb_ld(unsigned* p)              { return __hip_atomic_load(p, __ATOMIC_RELAXED, __HIP_MEMORY_SCOPE_AGENT); }
; __device__ __forceinline__ unsigned xb_add(unsigned* p, unsigned v) { return __hip_atomic_fetch_add(p, v, __ATOMIC_RELAXED, __HIP_MEMORY_SCOPE_AGENT); }
; __device__ __forceinline__ unsigned xb_xcc_id() { return (unsigned)__builtin_amdgcn_s_getreg((3 << 11) | 20) & 0xFu; }
; #define XB_SPIN(cond, bar) do { unsigned _sp = 0; while (cond) { __builtin_amdgcn_s_sleep(1); \
;     if ((++_sp & 255u) == 0u) { if (xb_ld(&(bar)[XB_TMO])) break; if (_sp > XB_SPIN_CAP) { atomicAdd(&(bar)[XB_TMO], 1u); break; } } } } while (0)
; __device__ __forceinline__ bool is_leader(int wave_s) { int lane; asm volatile("v_mbcnt_lo_u32_b32 %0, -1, 0\n\tv_mbcnt_hi_u32_b32 %0, -1, %0" : "=v"(lane)); return wave_s == 0 && lane == 0; }
; __device__ __forceinline__ void grid_bar(unsigned* bar, volatile LAS unsigned* st, int wave_s, unsigned G) {
;     asm volatile("s_waitcnt vmcnt(0) lgkmcnt(0)" ::: "memory");
;     __syncthreads();
;     if (is_leader(wave_s)) {
;         const unsigned x = xb_xcc_id();
;         unsigned nloc = st[0], nx = st[1];
;         if (nloc == 0u) { xcd_barrier_complete(bar, x, G, nloc, nx); st[0] = nloc; st[1] = nx; }
;         const unsigned old = xb_add(&bar[XB_XSUB(x)], 1u);
;         const unsigned gen = old / nloc;
;         if (old + 1u == (gen + 1u) * nloc) {
;             __builtin_amdgcn_fence(__ATOMIC_RELEASE, "agent");
;             asm volatile("s_waitcnt vmcnt(0)" ::: "memory");
;             const unsigned og = xb_add(&bar[XB_TOP], 1u);
;             const unsigned tg = og / nx;
;             if (og + 1u == (tg + 1u) * nx) xb_add(&bar[XB_TOPGEN], 1u);
;             else XB_SPIN(xb_ld(&bar[XB_TOPGEN]) == tg, bar);
;             __builtin_amdgcn_fence(__ATOMIC_ACQUIRE, "agent");
;             xb_add(&bar[XB_XGEN(x)], 1u);
;             asm volatile("s_waitcnt vmcnt(0)" ::: "memory");
;         } else {
;             XB_SPIN(xb_ld(&bar[XB_XGEN(x)]) == gen, bar);
;             __builtin_amdgcn_fence(__ATOMIC_ACQUIRE, "agent");
;             asm volatile("s_waitcnt vmcnt(0)" ::: "memory");
;         }
;     }
;     __syncthreads();
; }
.LBB0_1832:
	s_mov_b32 s2, s94
	s_mov_b32 s4, s95
	s_cmp_lt_i32 s2, 19
	s_cselect_b64 s[2:3], -1, 0
	s_cmp_gt_i32 s4, 18
	s_cselect_b64 s[4:5], -1, 0
	s_and_b64 s[2:3], s[2:3], s[4:5]
	s_andn2_b64 vcc, exec, s[2:3]
	s_cbranch_vccnz .LBB0_1887
	s_mov_b32 s2, s94
	s_mov_b32 s4, s95
	s_cmp_lt_i32 s2, 20
	s_cselect_b64 s[2:3], -1, 0
	s_cmp_gt_i32 s4, 19
	s_cselect_b64 s[4:5], -1, 0
	s_and_b64 s[2:3], s[2:3], s[4:5]
	s_andn2_b64 vcc, exec, s[2:3]
	s_cbranch_vccnz .LBB0_1887
	s_cmp_lt_u32 s79, 64
	s_waitcnt vmcnt(0) lgkmcnt(0)
	s_cselect_b64 s[2:3], -1, 0
	s_waitcnt vmcnt(0) lgkmcnt(0)
	s_barrier
	v_mbcnt_lo_u32_b32 v0, -1, 0
	v_mbcnt_hi_u32_b32 v0, -1, v0
	s_nop 0
	v_cmp_eq_u32_e32 vcc, 0, v0
	s_and_b64 s[4:5], s[2:3], vcc
	s_and_saveexec_b64 s[2:3], s[4:5]
	s_cbranch_execz .LBB0_1886
	s_cmp_eq_u32 s98, 0
	s_cbranch_scc1 .Lgl_10
	s_load_dwordx2 s[4:5], s[0:1], 0xf0
	s_and_b32 s6, s78, 7
	s_lshl_b32 s6, s6, 8
	s_lshr_b32 s7, s92, 3
	s_mul_i32 s7, s7, 10
	v_mov_b32_e32 v0, s6
	v_mov_b32_e32 v1, 1
	s_waitcnt lgkmcnt(0)
	global_atomic_add v2, v0, v1, s[4:5] offset:1152 sc0
	buffer_inv sc1
	s_waitcnt vmcnt(0)
	v_readfirstlane_b32 s8, v2
	s_add_i32 s8, s8, 1
	s_cmp_eq_u32 s8, s7
	s_cbranch_scc0 .Lwt_10
	global_atomic_add v0, v1, s[4:5] offset:1216
	s_branch .Lac_10

; #define LAS __attribute__((address_space(3)))
; __device__ __forceinline__ unsigned xb_ld(unsigned* p)              { return __hip_atomic_load(p, __ATOMIC_RELAXED, __HIP_MEMORY_SCOPE_AGENT); }
; __device__ __forceinline__ unsigned xb_add(unsigned* p, unsigned v) { return __hip_atomic_fetch_add(p, v, __ATOMIC_RELAXED, __HIP_MEMORY_SCOPE_AGENT); }
; __device__ __forceinline__ unsigned xb_xcc_id() { return (unsigned)__builtin_amdgcn_s_getreg((3 << 11) | 20) & 0xFu; }
; #define XB_SPIN(cond, bar) do { unsigned _sp = 0; while (cond) { __builtin_amdgcn_s_sleep(1); \
;     if ((++_sp & 255u) == 0u) { if (xb_ld(&(bar)[XB_TMO])) break; if (_sp > XB_SPIN_CAP) { atomicAdd(&(bar)[XB_TMO], 1u); break; } } } } while (0)
; __device__ __forceinline__ bool is_leader(int wave_s) { int lane; asm volatile("v_mbcnt_lo_u32_b32 %0, -1, 0\n\tv_mbcnt_hi_u32_b32 %0, -1, %0" : "=v"(lane)); return wave_s == 0 && lane == 0; }
; __device__ __forceinline__ void grid_bar(unsigned* bar, volatile LAS unsigned* st, int wave_s, unsigned G) {
;     asm volatile("s_waitcnt vmcnt(0) lgkmcnt(0)" ::: "memory");
;     __syncthreads();
;     if (is_leader(wave_s)) {
;         const unsigned x = xb_xcc_id();
;         unsigned nloc = st[0], nx = st[1];
;         if (nloc == 0u) { xcd_barrier_complete(bar, x, G, nloc, nx); st[0] = nloc; st[1] = nx; }
;         const unsigned old = xb_add(&bar[XB_XSUB(x)], 1u);
;         const unsigned gen = old / nloc;
;         if (old + 1u == (gen + 1u) * nloc) {
;             __builtin_amdgcn_fence(__ATOMIC_RELEASE, "agent");
;             asm volatile("s_waitcnt vmcnt(0)" ::: "memory");
;             const unsigned og = xb_add(&bar[XB_TOP], 1u);
;             const unsigned tg = og / nx;
;             if (og + 1u == (tg + 1u) * nx) xb_add(&bar[XB_TOPGEN], 1u);
;             else XB_SPIN(xb_ld(&bar[XB_TOPGEN]) == tg, bar);
;             __builtin_amdgcn_fence(__ATOMIC_ACQUIRE, "agent");
;             xb_add(&bar[XB_XGEN(x)], 1u);
;             asm volatile("s_waitcnt vmcnt(0)" ::: "memory");
;         } else {
;             XB_SPIN(xb_ld(&bar[XB_XGEN(x)]) == gen, bar);
;             __builtin_amdgcn_fence(__ATOMIC_ACQUIRE, "agent");
;             asm volatile("s_waitcnt vmcnt(0)" ::: "memory");
;         }
;     }
;     __syncthreads();
; }
.LBB0_1962:
	s_mov_b32 s2, s94
	s_mov_b32 s4, s95
	s_cmp_lt_i32 s2, 20
	s_cselect_b64 s[2:3], -1, 0
	s_cmp_gt_i32 s4, 19
	s_cselect_b64 s[4:5], -1, 0
	s_and_b64 s[2:3], s[2:3], s[4:5]
	s_andn2_b64 vcc, exec, s[2:3]
	s_cbranch_vccnz .LBB0_2017
	s_mov_b32 s2, s94
	s_mov_b32 s4, s95
	s_cmp_lt_i32 s2, 21
	s_cselect_b64 s[2:3], -1, 0
	s_cmp_gt_i32 s4, 20
	s_cselect_b64 s[4:5], -1, 0
	s_and_b64 s[2:3], s[2:3], s[4:5]
	s_andn2_b64 vcc, exec, s[2:3]
	s_cbranch_vccnz .LBB0_2017
	s_cmp_lt_u32 s79, 64
	s_waitcnt vmcnt(0) lgkmcnt(0)
	s_cselect_b64 s[2:3], -1, 0
	s_waitcnt vmcnt(0) lgkmcnt(0)
	s_barrier
	v_mbcnt_lo_u32_b32 v0, -1, 0
	v_mbcnt_hi_u32_b32 v0, -1, v0
	s_nop 0
	v_cmp_eq_u32_e32 vcc, 0, v0
	s_and_b64 s[4:5], s[2:3], vcc
	s_and_saveexec_b64 s[2:3], s[4:5]
	s_cbranch_execz .LBB0_2016
	s_cmp_eq_u32 s98, 0
	s_cbranch_scc1 .Lgl_11
	s_load_dwordx2 s[4:5], s[0:1], 0xf0
	s_and_b32 s6, s78, 7
	s_lshl_b32 s6, s6, 8
	s_lshr_b32 s7, s92, 3
	s_mul_i32 s7, s7, 11
	v_mov_b32_e32 v0, s6
	v_mov_b32_e32 v1, 1
	s_waitcnt lgkmcnt(0)
	global_atomic_add v2, v0, v1, s[4:5] offset:1152 sc0
	buffer_inv sc1
	s_waitcnt vmcnt(0)
	v_readfirstlane_b32 s8, v2
	s_add_i32 s8, s8, 1
	s_cmp_eq_u32 s8, s7
	s_cbranch_scc0 .Lwt_11
	global_atomic_add v0, v1, s[4:5] offset:1216
	s_branch .Lac_11
.Lwt_11:
	s_sleep 1
	global_load_dword v2, v0, s[4:5] offset:1216 sc1
	s_waitcnt vmcnt(0)
	v_readfirstlane_b32 s8, v2
	s_cmp_lt_u32 s8, 11
	s_cbranch_scc1 .Lwt_11
